# rebalance hosted expert-table quantisation: layer-0 MoBA phase hosts tables of layers 0-1, layer-2 MoBA phase hosts tables of layers 2-3 (was 0-2 / 3)
# speedup vs baseline: 1.0075x; 1.0019x over previous
; template <int MI, bool SWAP, bool F8 = false>
; __device__ __forceinline__ void gemm_core(const bf16_t* __restrict__ A, int lda, const bf16_t* __restrict__ B, int ldb,
;                                           int K, char* smem, f32x4 (&acc)[MI][4]) {
;     ...
;   const bf16_t* ap = A + (size_t)lr * lda + lc * 8;
;   const bf16_t* bp = B + (size_t)lr * ldb + lc * 8;
; #pragma unroll
;   for (int i = 0; i < MI; ++i)
; #pragma unroll
;     for (int j = 0; j < 4; ++j) acc[i][j] = (f32x4){0.f, 0.f, 0.f, 0.f};
;   const int nk = K >> 6;
; #pragma unroll
;   for (int i = 0; i < MI; ++i) ra[i] = *(const u32x4*)(ap + (size_t)(32 * i) * lda);
; #pragma unroll
;   for (int i = 0; i < 4; ++i) rb[i] = *(const u32x4*)(bp + (size_t)(32 * i) * ldb);
;   const int woff = lr * 128 + ((lc ^ (lr & 7)) << 4);
;   const int xrow = (wm * 16 * MI + li) * 128;
;   const int wrow = 32768 + (wn * 32 + li) * 128;
;   for (int kt = 0; kt < nk; ++kt) {
;     __syncthreads();
; #pragma unroll
;     for (int i = 0; i < MI; ++i) *(u32x4*)(smem + woff + i * 4096) = ra[i];
; #pragma unroll
;     for (int i = 0; i < 4; ++i) *(u32x4*)(smem + 32768 + woff + i * 4096) = rb[i];
;     __syncthreads();
;     if (kt + 1 < nk) {
; #pragma unroll
;       for (int i = 0; i < MI; ++i) ra[i] = *(const u32x4*)(ap + (size_t)(32 * i) * lda + (kt + 1) * 64);
; #pragma unroll
;       for (int i = 0; i < 4; ++i) rb[i] = *(const u32x4*)(bp + (size_t)(32 * i) * ldb + (kt + 1) * 64);
; __global__ void __launch_bounds__(256, 2) fwd_kernel(P p) {
;     ...
;         for (int it = blockIdx.x; it < 512; it += G) {
;           const int lf = it >> 7, hp = (it >> 3) & 15, kc = it & 7;
;           gemm_tile_fp8out<4>((const bf16_t*)(ws + OFF_SUBK) + ((size_t)lf * 16 + hp) * 16384, 128,
;                               (const bf16_t*)(ws + OFF_AO) + (size_t)lf * 1024 * 2048 + (size_t)(kc * 128) * 2048 + hp * 128, 2048, 128,
;                               (unsigned char*)(ws + OFF_WPQ) + ((size_t)lf * 2048 + hp * 128) * 1024 + kc * 128, 1024, 256.f, smem);
;     ...
;       const int qb = (layer == 0) ? 16384 : 49152, qe = (layer == 0) ? 49152 : 65536;
.LBB0_383:
	v_readlane_b32 s0, v255, 60
	v_readlane_b32 s1, v255, 61
	s_cmp_lg_u32 s0, 0
	s_cselect_b64 s[0:1], -1, 0
	s_and_b64 s[6:7], s[0:1], exec
	s_mov_b32 s6, 0x8000
	s_cselect_b32 s19, 0x10000, s6
	s_cselect_b32 s36, s6, 0
	v_readlane_b32 s6, v255, 38
	v_readlane_b32 s7, v255, 39
	s_or_b64 s[0:1], s[0:1], s[6:7]
	s_and_b64 vcc, exec, s[0:1]
	s_cbranch_vccnz .LBB0_387
	s_add_u32 s6, s12, 0x3884000
	s_addc_u32 s7, s13, 0
	s_add_u32 s8, s12, 0x25a84000
	s_addc_u32 s9, s13, 0
	s_add_u32 s10, s12, 0x2884000
	v_readlane_b32 s0, v255, 53
	s_addc_u32 s11, s13, 0
	v_readlane_b32 s19, v255, 52
	s_mov_b32 s20, s0
	s_mov_b32 s27, 0x60000
	s_movk_i32 s28, 0x2000
	s_movk_i32 s29, 0xffc0
	s_movk_i32 s30, 0x4000
	s_mov_b32 s31, 0x1ffffc0
	v_readlane_b32 s1, v255, 54
.LBB0_385:
	s_ashr_i32 s0, s20, 7
	s_ashr_i32 s1, s0, 31
	s_bfe_u32 s21, s20, 0x40003
	s_lshl_b64 s[22:23], s[0:1], 19
	s_add_u32 s22, s6, s22
	s_waitcnt vmcnt(14)
	v_mov_b32_e32 v92, v208
	s_addc_u32 s23, s7, s23
	s_lshl_b32 s24, s21, 15
	s_add_u32 s22, s22, s24
	v_ashrrev_i32_e32 v2, 3, v92
	v_ashrrev_i32_e32 v3, 31, v2
	s_addc_u32 s23, s23, 0
	s_lshl_b64 s[24:25], s[0:1], 22
	v_lshlrev_b32_e32 v0, 4, v92
	v_lshlrev_b32_e32 v23, 7, v2
	v_xor_b32_e32 v24, v2, v92
	v_lshlrev_b64 v[40:41], 12, v[2:3]
	v_lshlrev_b64 v[2:3], 8, v[2:3]
	s_add_u32 s24, s8, s24
	v_and_b32_e32 v21, 15, v92
	v_lshrrev_b32_e32 v22, 1, v92
	v_and_b32_e32 v0, 0x70, v0
	v_lshl_add_u64 v[2:3], s[22:23], 0, v[2:3]
	s_addc_u32 s23, s9, s25
	s_and_b32 s22, s19, 0x380
	v_lshrrev_b32_e32 v20, 4, v92
	v_and_b32_e32 v93, 7, v92
	v_and_or_b32 v25, v22, s31, v21
	v_and_or_b32 v21, v22, 32, v21
	v_lshlrev_b32_e32 v22, 4, v24
	v_lshl_add_u64 v[2:3], v[2:3], 0, v[0:1]
	s_lshl_b32 s25, s22, 12
	v_bitop3_b32 v20, v20, v93, 3 bitop3:0x6c
	v_and_or_b32 v134, v22, s33, v23
	v_add_co_u32_e32 v22, vcc, s28, v2
	s_add_u32 s24, s24, s25
	v_lshlrev_b32_e32 v94, 7, v25
	v_lshlrev_b32_e32 v95, 7, v21
	v_lshlrev_b32_e32 v20, 4, v20
	v_addc_co_u32_e32 v23, vcc, 0, v3, vcc
	s_addc_u32 s23, s23, 0
	s_lshl_b32 s25, s21, 8
	v_or_b32_e32 v135, v95, v20
	v_or_b32_e32 v136, v94, v20
	v_add_co_u32_e32 v20, vcc, s30, v2
	s_add_u32 s24, s24, s25
	s_nop 0
	v_addc_co_u32_e32 v21, vcc, 0, v3, vcc
	s_movk_i32 s26, 0x6000
	s_addc_u32 s25, s23, 0
	s_waitcnt vmcnt(10)
	v_add_co_u32_e32 v120, vcc, s26, v2
	v_lshl_add_u64 v[40:41], s[24:25], 0, v[40:41]
	s_nop 0
	v_addc_co_u32_e32 v121, vcc, 0, v3, vcc
	s_waitcnt vmcnt(9)
	v_lshl_add_u64 v[124:125], v[40:41], 0, v[0:1]
	v_add_co_u32_e32 v126, vcc, s46, v124
	global_load_dwordx4 v[24:27], v[2:3], off
	s_nop 0
	v_addc_co_u32_e32 v127, vcc, 0, v125, vcc
	s_waitcnt vmcnt(9)
	v_add_co_u32_e32 v128, vcc, s50, v124
	global_load_dwordx4 v[28:31], v[22:23], off
	global_load_dwordx4 v[32:35], v[20:21], off
	global_load_dwordx4 v[36:39], v[120:121], off
	v_addc_co_u32_e32 v129, vcc, 0, v125, vcc
	v_add_co_u32_e32 v132, vcc, s27, v124
	v_bfe_u32 v0, v92, 4, 2
	s_nop 0
	v_addc_co_u32_e32 v133, vcc, 0, v125, vcc
	global_load_dwordx4 v[40:43], v[124:125], off
	global_load_dwordx4 v[44:47], v[126:127], off
	global_load_dwordx4 v[48:51], v[128:129], off
	global_load_dwordx4 v[52:55], v[132:133], off
	s_waitcnt vmcnt(63) expcnt(7) lgkmcnt(15)
	s_barrier
	v_bitop3_b32 v0, v0, v93, 4 bitop3:0x36
	v_lshlrev_b32_e32 v0, 4, v0
	v_or_b32_e32 v137, v95, v0
	v_or_b32_e32 v0, v94, v0
	s_lshl_b64 s[0:1], s[0:1], 21
	s_lshl_b32 s21, s21, 17
	s_add_u32 s0, s10, s0
	s_addc_u32 s1, s11, s1
	s_add_u32 s0, s0, s21
	s_addc_u32 s1, s1, 0
	s_add_u32 s0, s0, s22
	s_addc_u32 s1, s1, 0
	s_add_i32 s20, s20, s78
	s_add_i32 s19, s19, s77
	s_cmpk_lt_i32 s20, 0x200
	s_waitcnt vmcnt(7)
	ds_write_b128 v134, v[24:27]
	s_waitcnt vmcnt(6)
	ds_write_b128 v134, v[28:31] offset:4096
	s_waitcnt vmcnt(5)
	ds_write_b128 v134, v[32:35] offset:8192
	s_waitcnt vmcnt(4)
	ds_write_b128 v134, v[36:39] offset:12288
	s_waitcnt vmcnt(3)
	ds_write_b128 v134, v[40:43] offset:32768
	s_waitcnt vmcnt(2)
	ds_write_b128 v134, v[44:47] offset:36864
	s_waitcnt vmcnt(1)
	ds_write_b128 v134, v[48:51] offset:40960
	s_waitcnt vmcnt(0)
	ds_write_b128 v134, v[52:55] offset:45056
	s_waitcnt lgkmcnt(0)
	s_barrier
	ds_read_b128 v[24:27], v135 offset:32768
	ds_read_b128 v[28:31], v135 offset:34816
	ds_read_b128 v[32:35], v136
	ds_read_b128 v[36:39], v136 offset:2048
	ds_read_b128 v[44:47], v135 offset:40960
	ds_read_b128 v[52:55], v135 offset:43008
	ds_read_b128 v[72:75], v136 offset:4096
	ds_read_b128 v[76:79], v136 offset:6144
	s_waitcnt lgkmcnt(5)
	v_mfma_f32_16x16x32_bf16 v[40:43], v[24:27], v[32:35], 0
	ds_read_b128 v[92:95], v137 offset:32768
	ds_read_b128 v[96:99], v137 offset:34816
	v_mfma_f32_16x16x32_bf16 v[48:51], v[28:31], v[32:35], 0
	s_waitcnt lgkmcnt(5)
	v_mfma_f32_16x16x32_bf16 v[56:59], v[44:47], v[32:35], 0
	s_waitcnt lgkmcnt(4)
	v_mfma_f32_16x16x32_bf16 v[32:35], v[52:55], v[32:35], 0
	v_mfma_f32_16x16x32_bf16 v[60:63], v[24:27], v[36:39], 0
	v_mfma_f32_16x16x32_bf16 v[64:67], v[28:31], v[36:39], 0
	v_mfma_f32_16x16x32_bf16 v[68:71], v[44:47], v[36:39], 0
	v_mfma_f32_16x16x32_bf16 v[36:39], v[52:55], v[36:39], 0
	s_waitcnt lgkmcnt(3)
	v_mfma_f32_16x16x32_bf16 v[80:83], v[24:27], v[72:75], 0
	v_mfma_f32_16x16x32_bf16 v[84:87], v[28:31], v[72:75], 0
	v_mfma_f32_16x16x32_bf16 v[88:91], v[44:47], v[72:75], 0
	v_mfma_f32_16x16x32_bf16 v[72:75], v[52:55], v[72:75], 0
	s_waitcnt lgkmcnt(2)
	v_mfma_f32_16x16x32_bf16 v[24:27], v[24:27], v[76:79], 0
	v_mfma_f32_16x16x32_bf16 v[28:31], v[28:31], v[76:79], 0
	v_mfma_f32_16x16x32_bf16 v[44:47], v[44:47], v[76:79], 0
	v_mfma_f32_16x16x32_bf16 v[76:79], v[52:55], v[76:79], 0
	ds_read_b128 v[52:55], v0
	ds_read_b128 v[100:103], v0 offset:2048
	ds_read_b128 v[108:111], v137 offset:43008
	s_waitcnt lgkmcnt(2)
; template <int MI, bool SWAP, bool F8 = false>
; __device__ __forceinline__ void gemm_core(const bf16_t* __restrict__ A, int lda, const bf16_t* __restrict__ B, int ldb,
;                                           int K, char* smem, f32x4 (&acc)[MI][4]) {
;     ...
;   for (int kt = 0; kt < nk; ++kt) {
;     __syncthreads();
; #pragma unroll
;     for (int i = 0; i < MI; ++i) *(u32x4*)(smem + woff + i * 4096) = ra[i];
; #pragma unroll
;     for (int i = 0; i < 4; ++i) *(u32x4*)(smem + 32768 + woff + i * 4096) = rb[i];
;     __syncthreads();
;     if (kt + 1 < nk) {
; #pragma unroll
;       for (int i = 0; i < MI; ++i) ra[i] = *(const u32x4*)(ap + (size_t)(32 * i) * lda + (kt + 1) * 64);
; #pragma unroll
;       for (int i = 0; i < 4; ++i) rb[i] = *(const u32x4*)(bp + (size_t)(32 * i) * ldb + (kt + 1) * 64);
;     }
;     if (F8) {
;       const int c0 = (g ^ (li & 7)) << 4, c1 = ((4 + g) ^ (li & 7)) << 4;
;       i32x8 wf8[4];
; #pragma unroll
;       for (int j = 0; j < 4; ++j) {
;         const char* rp = smem + wrow + ((j & 1) * 16 + (j >> 1) * 64) * 128;
;         const u32x4 lo = *(const u32x4*)(rp + c0), hi = *(const u32x4*)(rp + c1);
;         wf8[j] = (i32x8){(int)lo.x, (int)lo.y, (int)lo.z, (int)lo.w, (int)hi.x, (int)hi.y, (int)hi.z, (int)hi.w};
;       }
; #pragma unroll
;       for (int i = 0; i < MI; ++i) {
;         const char* rp = smem + xrow + i * 2048;
;         const u32x4 lo = *(const u32x4*)(rp + c0), hi = *(const u32x4*)(rp + c1);
;         const i32x8 xf8 = {(int)lo.x, (int)lo.y, (int)lo.z, (int)lo.w, (int)hi.x, (int)hi.y, (int)hi.z, (int)hi.w};
; #pragma unroll
;         for (int j = 0; j < 4; ++j)
;           acc[i][j] = __builtin_amdgcn_mfma_scale_f32_16x16x128_f8f6f4(wf8[j], xf8, acc[i][j], 0, 0, 0, 0x77777777, 0, 0x7f7f7f7f);
;       }
;     } else {
; #pragma unroll
;     for (int kk = 0; kk < 2; ++kk) {
;       const int ch = ((kk * 4 + g) ^ (li & 7)) << 4;
;       bf16x8 xf[MI], wf[4];
; #pragma unroll
;       for (int j = 0; j < 4; ++j) wf[j] = *(const bf16x8*)(smem + wrow + ((j & 1) * 16 + (j >> 1) * 64) * 128 + ch);
; #pragma unroll
;       for (int i = 0; i < MI; ++i) xf[i] = *(const bf16x8*)(smem + xrow + i * 2048 + ch);
; #pragma unroll
;       for (int i = 0; i < MI; ++i)
; #pragma unroll
;         for (int j = 0; j < 4; ++j) {
	v_mfma_f32_16x16x32_bf16 v[104:107], v[92:95], v[52:55], v[40:43]
	s_nop 2
	ds_read_b128 v[40:43], v137 offset:40960
	s_waitcnt lgkmcnt(0)
	v_mfma_f32_16x16x32_bf16 v[112:115], v[40:43], v[52:55], v[56:59]
	v_mfma_f32_16x16x32_bf16 v[116:119], v[92:95], v[100:103], v[60:63]
	v_mfma_f32_16x16x32_bf16 v[64:67], v[96:99], v[100:103], v[64:67]
	v_mfma_f32_16x16x32_bf16 v[68:71], v[40:43], v[100:103], v[68:71]
	v_mfma_f32_16x16x32_bf16 v[100:103], v[108:111], v[100:103], v[36:39]
	s_nop 2
	ds_read_b128 v[36:39], v0 offset:4096
	ds_read_b128 v[56:59], v0 offset:6144
	global_load_dwordx4 v[60:63], v[22:23], off offset:128
	s_waitcnt lgkmcnt(1)
	v_mfma_f32_16x16x32_bf16 v[80:83], v[92:95], v[36:39], v[80:83]
	v_mfma_f32_16x16x32_bf16 v[84:87], v[96:99], v[36:39], v[84:87]
	v_mfma_f32_16x16x32_bf16 v[88:91], v[40:43], v[36:39], v[88:91]
	v_mfma_f32_16x16x32_bf16 v[72:75], v[108:111], v[36:39], v[72:75]
	global_load_dwordx4 v[36:39], v[2:3], off offset:128
	s_nop 0
	global_load_dwordx4 v[120:123], v[120:121], off offset:128
	s_nop 0
	global_load_dwordx4 v[20:23], v[20:21], off offset:128
	v_mov_b32_e32 v2, v208
	s_waitcnt lgkmcnt(0)
	v_mfma_f32_16x16x32_bf16 v[92:95], v[92:95], v[56:59], v[24:27]
	s_nop 2
	global_load_dwordx4 v[24:27], v[126:127], off offset:128
	s_nop 0
	global_load_dwordx4 v[124:127], v[124:125], off offset:128
	s_nop 0
	global_load_dwordx4 v[128:131], v[128:129], off offset:128
	v_mfma_f32_16x16x32_bf16 v[48:51], v[96:99], v[52:55], v[48:51]
	v_mfma_f32_16x16x32_bf16 v[32:35], v[108:111], v[52:55], v[32:35]
	v_mfma_f32_16x16x32_bf16 v[52:55], v[96:99], v[56:59], v[28:31]
	s_nop 2
	global_load_dwordx4 v[28:31], v[132:133], off offset:128
	v_mfma_f32_16x16x32_bf16 v[40:43], v[40:43], v[56:59], v[44:47]
	s_barrier
	v_mfma_f32_16x16x32_bf16 v[44:47], v[108:111], v[56:59], v[76:79]
	s_waitcnt vmcnt(6)
	ds_write_b128 v134, v[36:39]
	ds_write_b128 v134, v[60:63] offset:4096
	s_waitcnt vmcnt(4)
	ds_write_b128 v134, v[20:23] offset:8192
	ds_write_b128 v134, v[120:123] offset:12288
	s_waitcnt vmcnt(2)
	ds_write_b128 v134, v[124:127] offset:32768
	ds_write_b128 v134, v[24:27] offset:36864
	s_waitcnt vmcnt(1)
	ds_write_b128 v134, v[128:131] offset:40960
	s_waitcnt vmcnt(0)
	ds_write_b128 v134, v[28:31] offset:45056
	s_waitcnt lgkmcnt(0)
	s_barrier
	ds_read_b128 v[76:79], v135 offset:32768
	ds_read_b128 v[96:99], v135 offset:34816
	ds_read_b128 v[20:23], v136
	ds_read_b128 v[24:27], v136 offset:2048
	s_waitcnt lgkmcnt(1)
	v_mfma_f32_16x16x32_bf16 v[56:59], v[76:79], v[20:23], v[104:107]
	s_nop 2
	ds_read_b128 v[104:107], v135 offset:40960
	ds_read_b128 v[108:111], v135 offset:43008
	v_mov_b32_e32 v120, v1
	v_mfma_f32_16x16x32_bf16 v[60:63], v[96:99], v[20:23], v[48:51]
	v_mov_b32_e32 v121, v1
	v_mov_b32_e32 v122, v1
	v_mov_b32_e32 v123, v1
	s_waitcnt lgkmcnt(0)
	v_mfma_f32_16x16x32_bf16 v[48:51], v[108:111], v[20:23], v[32:35]
	v_mov_b32_e32 v124, v1
	v_mov_b32_e32 v125, v1
	v_mov_b32_e32 v126, v1
	v_mfma_f32_16x16x32_bf16 v[32:35], v[96:99], v[24:27], v[64:67]
	v_mov_b32_e32 v127, v1
	v_mov_b32_e32 v128, v1
	v_mov_b32_e32 v129, v1
	v_mfma_f32_16x16x32_bf16 v[28:31], v[104:107], v[24:27], v[68:71]
	ds_read_b128 v[64:67], v136 offset:4096
	s_nop 1
	ds_read_b128 v[68:71], v136 offset:6144
	v_mov_b32_e32 v130, v1
	v_mov_b32_e32 v131, v1
	v_mfma_f32_16x16x32_bf16 v[112:115], v[104:107], v[20:23], v[112:115]
	v_mfma_f32_16x16x32_bf16 v[36:39], v[76:79], v[24:27], v[116:119]
	v_mfma_f32_16x16x32_bf16 v[24:27], v[108:111], v[24:27], v[100:103]
	s_nop 1
	v_mov_b32_e32 v116, v1
	v_mov_b32_e32 v117, v1
	v_mov_b32_e32 v118, v1
	s_waitcnt lgkmcnt(1)
	v_mfma_f32_16x16x32_bf16 v[20:23], v[76:79], v[64:67], v[80:83]
	v_mov_b32_e32 v119, v1
	v_mfma_f32_16x16x32_bf16 v[80:83], v[96:99], v[64:67], v[84:87]
	v_mfma_f32_16x16x32_bf16 v[84:87], v[104:107], v[64:67], v[88:91]
	v_mfma_f32_16x16x32_bf16 v[64:67], v[108:111], v[64:67], v[72:75]
	s_waitcnt lgkmcnt(0)
	v_mfma_f32_16x16x32_bf16 v[72:75], v[76:79], v[68:71], v[92:95]
	ds_read_b128 v[76:79], v137 offset:32768
	ds_read_b128 v[88:91], v137 offset:34816
	v_mfma_f32_16x16x32_bf16 v[52:55], v[96:99], v[68:71], v[52:55]
	v_mfma_f32_16x16x32_bf16 v[40:43], v[104:107], v[68:71], v[40:43]
	v_mfma_f32_16x16x32_bf16 v[44:47], v[108:111], v[68:71], v[44:47]
	ds_read_b128 v[68:71], v0
	ds_read_b128 v[92:95], v0 offset:2048
	ds_read_b128 v[96:99], v137 offset:40960
	ds_read_b128 v[100:103], v137 offset:43008
	s_waitcnt lgkmcnt(3)
	v_mfma_f32_16x16x32_bf16 v[56:59], v[76:79], v[68:71], v[56:59]
	v_mfma_f32_16x16x32_bf16 v[60:63], v[88:91], v[68:71], v[60:63]
	s_waitcnt lgkmcnt(1)
	v_mfma_f32_16x16x32_bf16 v[104:107], v[96:99], v[68:71], v[112:115]
	s_waitcnt lgkmcnt(0)
	v_mfma_f32_16x16x32_bf16 v[48:51], v[100:103], v[68:71], v[48:51]
	ds_read_b128 v[68:71], v0 offset:4096
	ds_read_b128 v[108:111], v0 offset:6144
	s_nop 0
	v_and_b32_e32 v0, 15, v2
	v_ashrrev_i32_e32 v3, 1, v2
	v_mfma_f32_16x16x32_bf16 v[36:39], v[76:79], v[92:95], v[36:39]
	s_nop 1
	v_mul_f32_e32 v48, 0x43800000, v48
	v_mul_f32_e32 v49, 0x43800000, v49
	v_cvt_pk_fp8_f32 v119, v48, v49
	v_mfma_f32_16x16x32_bf16 v[32:35], v[88:91], v[92:95], v[32:35]
	v_mul_f32_e32 v50, 0x43800000, v50
	s_nop 0
	v_mul_f32_e32 v36, 0x43800000, v36
	v_mul_f32_e32 v37, 0x43800000, v37
	v_mfma_f32_16x16x32_bf16 v[28:31], v[96:99], v[92:95], v[28:31]
	v_cvt_pk_fp8_f32 v120, v36, v37
	s_nop 1
	v_mul_f32_e32 v32, 0x43800000, v32
	v_mul_f32_e32 v33, 0x43800000, v33
	v_mfma_f32_16x16x32_bf16 v[24:27], v[100:103], v[92:95], v[24:27]
	v_lshrrev_b32_e32 v92, 1, v2
	v_lshrrev_b32_e32 v93, 2, v2
	v_and_or_b32 v2, v3, s29, v0
	v_and_b32_e32 v0, 32, v92
	v_or_b32_e32 v92, 16, v2
	v_or_b32_e32 v94, 32, v2
	v_or_b32_e32 v112, 48, v2
	v_and_or_b32 v0, v93, 12, v0
	v_ashrrev_i32_e32 v3, 31, v2
	v_ashrrev_i32_e32 v93, 31, v92
	v_ashrrev_i32_e32 v95, 31, v94
	v_ashrrev_i32_e32 v113, 31, v112
	s_waitcnt lgkmcnt(1)
; template <int MI>
; __device__ void gemm_tile_fp8out(const bf16_t* A, int lda, const bf16_t* B, int ldb, int K, unsigned char* C, int ldc, float mul, char* smem) {
;   f32x4 acc[MI][4];
;   gemm_core<MI, false>(A, lda, B, ldb, K, smem, acc);
;   EPI_COORDS
; #pragma unroll
;   for (int i = 0; i < MI; ++i)
; #pragma unroll
;     for (int j = 0; j < 4; ++j) {
;       int wd = __builtin_amdgcn_cvt_pk_fp8_f32(acc[i][j][0] * mul, acc[i][j][1] * mul, 0, false);
;       wd = __builtin_amdgcn_cvt_pk_fp8_f32(acc[i][j][2] * mul, acc[i][j][3] * mul, wd, true);
;       *(int*)(C + (size_t)MROW(i) * ldc + NCOL(j)) = wd;
;     }
; __global__ void __launch_bounds__(256, 2) fwd_kernel(P p) {
;     ...
;       const int qb = (layer == 0) ? 16384 : 49152, qe = (layer == 0) ? 49152 : 65536;
	v_mfma_f32_16x16x32_bf16 v[20:23], v[76:79], v[68:71], v[20:23]
	v_lshlrev_b64 v[2:3], 10, v[2:3]
	v_lshlrev_b64 v[92:93], 10, v[92:93]
	v_lshl_add_u64 v[2:3], s[0:1], 0, v[2:3]
	v_mfma_f32_16x16x32_bf16 v[80:83], v[88:91], v[68:71], v[80:83]
	v_lshl_add_u64 v[2:3], v[2:3], 0, v[0:1]
	v_mul_f32_e32 v28, 0x43800000, v28
	v_mul_f32_e32 v29, 0x43800000, v29
	v_mfma_f32_16x16x32_bf16 v[84:87], v[96:99], v[68:71], v[84:87]
	v_mul_f32_e32 v24, 0x43800000, v24
	v_mul_f32_e32 v25, 0x43800000, v25
	v_mul_f32_e32 v20, 0x43800000, v20
	v_mfma_f32_16x16x32_bf16 v[64:67], v[100:103], v[68:71], v[64:67]
	v_mul_f32_e32 v21, 0x43800000, v21
	v_mul_f32_e32 v80, 0x43800000, v80
	v_mul_f32_e32 v81, 0x43800000, v81
	s_waitcnt lgkmcnt(0)
	v_mfma_f32_16x16x32_bf16 v[68:71], v[76:79], v[108:111], v[72:75]
	v_lshl_add_u64 v[76:77], s[0:1], 0, v[92:93]
	v_lshl_add_u64 v[76:77], v[76:77], 0, v[0:1]
	v_mul_f32_e32 v78, 0x43800000, v105
	v_lshlrev_b64 v[72:73], 10, v[94:95]
	v_lshlrev_b64 v[74:75], 10, v[112:113]
	v_lshl_add_u64 v[72:73], s[0:1], 0, v[72:73]
	v_lshl_add_u64 v[74:75], s[0:1], 0, v[74:75]
	v_mfma_f32_16x16x32_bf16 v[52:55], v[88:91], v[108:111], v[52:55]
	v_lshl_add_u64 v[72:73], v[72:73], 0, v[0:1]
	v_lshl_add_u64 v[74:75], v[74:75], 0, v[0:1]
	v_mul_f32_e32 v0, 0x43800000, v56
	v_mfma_f32_16x16x32_bf16 v[40:43], v[96:99], v[108:111], v[40:43]
	v_mul_f32_e32 v56, 0x43800000, v57
	v_mul_f32_e32 v57, 0x43800000, v58
	v_mul_f32_e32 v58, 0x43800000, v59
	v_mfma_f32_16x16x32_bf16 v[44:47], v[100:103], v[108:111], v[44:47]
	v_mul_f32_e32 v59, 0x43800000, v60
	v_mul_f32_e32 v60, 0x43800000, v61
	v_cvt_pk_fp8_f32 v116, v0, v56
	v_mul_f32_e32 v61, 0x43800000, v62
	v_mul_f32_e32 v62, 0x43800000, v63
	v_mul_f32_e32 v63, 0x43800000, v104
	v_cvt_pk_fp8_f32 v117, v59, v60
	v_cvt_pk_fp8_f32 v118, v63, v78
	v_mul_f32_e32 v84, 0x43800000, v84
	v_mul_f32_e32 v85, 0x43800000, v85
	v_mul_f32_e32 v64, 0x43800000, v64
	v_mul_f32_e32 v65, 0x43800000, v65
	v_mul_f32_e32 v68, 0x43800000, v68
	v_mul_f32_e32 v69, 0x43800000, v69
	v_mul_f32_e32 v52, 0x43800000, v52
	v_mul_f32_e32 v53, 0x43800000, v53
	v_mul_f32_e32 v40, 0x43800000, v40
	v_mul_f32_e32 v41, 0x43800000, v41
	v_mul_f32_e32 v44, 0x43800000, v44
	v_mul_f32_e32 v45, 0x43800000, v45
	v_cvt_pk_fp8_f32 v121, v32, v33
	v_cvt_pk_fp8_f32 v122, v28, v29
	v_cvt_pk_fp8_f32 v123, v24, v25
	v_cvt_pk_fp8_f32 v124, v20, v21
	v_cvt_pk_fp8_f32 v125, v80, v81
	v_cvt_pk_fp8_f32 v126, v84, v85
	v_cvt_pk_fp8_f32 v127, v64, v65
	v_cvt_pk_fp8_f32 v128, v68, v69
	v_cvt_pk_fp8_f32 v129, v52, v53
	v_cvt_pk_fp8_f32 v130, v40, v41
	v_cvt_pk_fp8_f32 v131, v44, v45
	v_cvt_pk_fp8_f32 v116, v57, v58 op_sel:[0,0,1]
	v_mul_f32_e32 v79, 0x43800000, v106
	v_mul_f32_e32 v88, 0x43800000, v107
	v_cvt_pk_fp8_f32 v117, v61, v62 op_sel:[0,0,1]
	v_mul_f32_e32 v51, 0x43800000, v51
	v_cvt_pk_fp8_f32 v118, v79, v88 op_sel:[0,0,1]
	v_mul_f32_e32 v38, 0x43800000, v38
	v_mul_f32_e32 v39, 0x43800000, v39
	v_mul_f32_e32 v34, 0x43800000, v34
	v_mul_f32_e32 v35, 0x43800000, v35
	v_mul_f32_e32 v30, 0x43800000, v30
	v_mul_f32_e32 v31, 0x43800000, v31
	v_mul_f32_e32 v26, 0x43800000, v26
	v_mul_f32_e32 v27, 0x43800000, v27
	v_mul_f32_e32 v22, 0x43800000, v22
	v_mul_f32_e32 v23, 0x43800000, v23
	v_mul_f32_e32 v82, 0x43800000, v82
	v_mul_f32_e32 v83, 0x43800000, v83
	v_mul_f32_e32 v86, 0x43800000, v86
	v_mul_f32_e32 v87, 0x43800000, v87
	v_mul_f32_e32 v66, 0x43800000, v66
	v_mul_f32_e32 v67, 0x43800000, v67
	v_mul_f32_e32 v70, 0x43800000, v70
	v_mul_f32_e32 v71, 0x43800000, v71
	v_mul_f32_e32 v54, 0x43800000, v54
	v_mul_f32_e32 v55, 0x43800000, v55
	v_mul_f32_e32 v42, 0x43800000, v42
	v_mul_f32_e32 v43, 0x43800000, v43
	v_mul_f32_e32 v46, 0x43800000, v46
	v_mul_f32_e32 v47, 0x43800000, v47
	v_cvt_pk_fp8_f32 v119, v50, v51 op_sel:[0,0,1]
	v_cvt_pk_fp8_f32 v120, v38, v39 op_sel:[0,0,1]
	v_cvt_pk_fp8_f32 v121, v34, v35 op_sel:[0,0,1]
	v_cvt_pk_fp8_f32 v122, v30, v31 op_sel:[0,0,1]
	v_cvt_pk_fp8_f32 v123, v26, v27 op_sel:[0,0,1]
	v_cvt_pk_fp8_f32 v124, v22, v23 op_sel:[0,0,1]
	v_cvt_pk_fp8_f32 v125, v82, v83 op_sel:[0,0,1]
	v_cvt_pk_fp8_f32 v126, v86, v87 op_sel:[0,0,1]
	v_cvt_pk_fp8_f32 v127, v66, v67 op_sel:[0,0,1]
	v_cvt_pk_fp8_f32 v128, v70, v71 op_sel:[0,0,1]
	v_cvt_pk_fp8_f32 v129, v54, v55 op_sel:[0,0,1]
	v_cvt_pk_fp8_f32 v130, v42, v43 op_sel:[0,0,1]
	v_cvt_pk_fp8_f32 v131, v46, v47 op_sel:[0,0,1]
	global_store_dword v[2:3], v116, off
	global_store_dword v[2:3], v117, off offset:16
	global_store_dword v[2:3], v118, off offset:64
	global_store_dword v[2:3], v119, off offset:80
	global_store_dword v[76:77], v120, off
	global_store_dword v[76:77], v121, off offset:16
	global_store_dword v[76:77], v122, off offset:64
	global_store_dword v[76:77], v123, off offset:80
	global_store_dword v[72:73], v124, off
	global_store_dword v[72:73], v125, off offset:16
	global_store_dword v[72:73], v126, off offset:64
	global_store_dword v[72:73], v127, off offset:80
	global_store_dword v[74:75], v128, off
	global_store_dword v[74:75], v129, off offset:16
	global_store_dword v[74:75], v130, off offset:64
	global_store_dword v[74:75], v131, off offset:80
	s_cbranch_scc1 .LBB0_385
	s_mov_b32 s19, 0x8000
	s_movk_i32 s36, 0
